# gather token groups XCD-contiguous (class blockIdx%8 owns the tokens of its GEMM tiles); GA0->QKV seam XCD-local as well
# baseline (speedup 1.0000x reference)
.LBB0_594:
	s_cmp_lt_i32 s56, 8
	s_cselect_b64 s[0:1], -1, 0
	s_and_b64 s[0:1], s[0:1], s[4:5]
	s_andn2_b64 vcc, exec, s[0:1]
	s_cbranch_vccnz .LBB0_619
	s_cmpk_gt_i32 s33, 0x7ff
	v_mbcnt_lo_u32_b32 v0, -1, 0
	v_mbcnt_hi_u32_b32 v0, -1, v0
	s_cbranch_scc1 .LBB0_619
	s_and_b32 s63, s2, 7
	s_lshl_b32 s63, s63, 8
	s_lshr_b32 s64, s2, 3
	s_lshl_b32 s64, s64, 3
	s_or_b32 s63, s63, s64
	s_and_b32 s64, s33, 7
	s_or_b32 s63, s63, s64

.LBB0_1075:
	s_cmp_lt_i32 s56, 16
	s_cselect_b64 s[0:1], -1, 0
	s_and_b64 s[0:1], s[0:1], s[4:5]
	s_andn2_b64 vcc, exec, s[0:1]
	s_cbranch_vccnz .LBB0_1083
	s_cmpk_gt_i32 s33, 0x7ff
	v_mbcnt_lo_u32_b32 v0, -1, 0
	v_mbcnt_hi_u32_b32 v0, -1, v0
	s_cbranch_scc1 .LBB0_1083
	s_and_b32 s63, s2, 7
	s_lshl_b32 s63, s63, 8
	s_lshr_b32 s64, s2, 3
	s_lshl_b32 s64, s64, 3
	s_or_b32 s63, s63, s64
	s_and_b32 s64, s33, 7
	s_or_b32 s63, s63, s64
